# store widening (7.3) via v_permlane16_swap: P1 gate-byte stores 16 dwordx2 -> 8 dwordx4 per tile, attention output stores 4 dwordx2 -> 2 dwordx4 per step
# speedup vs baseline: 1.0136x; 1.0021x over previous
; __device__ __forceinline__ float fast_rcp(float x) { return __builtin_amdgcn_rcpf(x); }
; __device__ __forceinline__ float fast_exp2(float x) { return __builtin_amdgcn_exp2f(x); }
; __device__ __forceinline__ float sigmoid_f(float x) { return fast_rcp(1.0f + fast_exp2(-1.4426950409f * x)); }
; __device__ __forceinline__ float gelu_tanh(float x) { const float t = x + 0.044715f * x * x * x; return x * fast_rcp(1.0f + fast_exp2(-2.3022081981f * t)); }
; __device__ __forceinline__ f32x4 gelu4(f32x4 v) { return (f32x4){gelu_tanh(v[0]), gelu_tanh(v[1]), gelu_tanh(v[2]), gelu_tanh(v[3])}; }
; __device__ __forceinline__ f32x4 sigm4(f32x4 v) { return (f32x4){sigmoid_f(v[0]), sigmoid_f(v[1]), sigmoid_f(v[2]), sigmoid_f(v[3])}; }
;     __device__ __forceinline__ void operator()(f32x4 (&acc)[2][2][4][2], const Unit& u, int wr, int wc, int fr, int fq) const {
;     ...
;                 for (int m = 0; m < 4; ++m) {
;                     const int row = row0 + ai * HALF + m * 16;
;                     float rstd = row_rstd(ss, row, fq); if (mode == 1) rstd *= 0.125f;
;                     bf16_t* rowp = base + (size_t)row * ldc + col0;
; #pragma unroll
;                     for (int bj = 0; bj < 2; ++bj) {
;                         f32x4 v0 = acc[ai][bj][m][0] * rstd, v1 = acc[ai][bj][m][1] * rstd;
;                         if (mode == 3) { u32x2 w; w.x = gate_q4(sigm4(v0)); w.y = gate_q4(sigm4(v1)); *(u32x2*)((unsigned char*)Gt + (size_t)row * 4096 + col0 + bj * 32) = w; continue; }
.Lp1e_gates:
	s_mov_b32 s38, 0xbfb8aa3b
	s_mov_b32 s39, 0xbfb8aa3b
	s_mov_b32 s40, 0x437f0000
	s_mov_b32 s41, 0x437f0000
	v_lshl_add_u32 v186, v184, 12, v185
	v_and_b32_e32 v187, 16, v241
	v_lshrrev_b32_e32 v185, 1, v187
	v_add3_u32 v186, v186, v187, v185
	v_pk_mul_f32 v[190:191], v[128:129], s[38:39]
	v_pk_mul_f32 v[192:193], v[130:131], s[38:39]
	v_pk_mul_f32 v[194:195], v[124:125], s[38:39]
	v_pk_mul_f32 v[196:197], v[126:127], s[38:39]
	v_exp_f32_e32 v190, v190
	v_exp_f32_e32 v191, v191
	v_exp_f32_e32 v192, v192
	v_exp_f32_e32 v193, v193
	v_exp_f32_e32 v194, v194
	v_exp_f32_e32 v195, v195
	v_exp_f32_e32 v196, v196
	v_exp_f32_e32 v197, v197
	v_pk_add_f32 v[190:191], v[190:191], s[42:43]
	v_pk_add_f32 v[192:193], v[192:193], s[42:43]
	v_pk_add_f32 v[194:195], v[194:195], s[42:43]
	v_pk_add_f32 v[196:197], v[196:197], s[42:43]
	v_rcp_f32_e32 v190, v190
	v_rcp_f32_e32 v191, v191
	v_rcp_f32_e32 v192, v192
	v_rcp_f32_e32 v193, v193
	v_rcp_f32_e32 v194, v194
	v_rcp_f32_e32 v195, v195
	v_rcp_f32_e32 v196, v196
	v_rcp_f32_e32 v197, v197
	v_pk_fma_f32 v[190:191], v[190:191], s[40:41], 0.5 op_sel_hi:[1,1,0]
	v_pk_fma_f32 v[192:193], v[192:193], s[40:41], 0.5 op_sel_hi:[1,1,0]
	v_pk_fma_f32 v[194:195], v[194:195], s[40:41], 0.5 op_sel_hi:[1,1,0]
	v_pk_fma_f32 v[196:197], v[196:197], s[40:41], 0.5 op_sel_hi:[1,1,0]
	v_cvt_u32_f32_e32 v190, v190
	v_cvt_u32_f32_e32 v191, v191
	v_cvt_u32_f32_e32 v192, v192
	v_cvt_u32_f32_e32 v193, v193
	v_cvt_u32_f32_e32 v194, v194
	v_cvt_u32_f32_e32 v195, v195
	v_cvt_u32_f32_e32 v196, v196
	v_cvt_u32_f32_e32 v197, v197
	v_lshl_or_b32 v190, v191, 8, v190
	v_lshl_or_b32 v192, v193, 8, v192
	v_lshl_or_b32 v194, v195, 8, v194
	v_lshl_or_b32 v196, v197, 8, v196
	v_lshl_or_b32 v206, v192, 16, v190
	v_lshl_or_b32 v207, v196, 16, v194
	v_pk_mul_f32 v[198:199], v[120:121], s[38:39]
	v_pk_mul_f32 v[200:201], v[122:123], s[38:39]
	v_pk_mul_f32 v[202:203], v[116:117], s[38:39]
	v_pk_mul_f32 v[204:205], v[118:119], s[38:39]
	v_exp_f32_e32 v198, v198
	v_exp_f32_e32 v199, v199
	v_exp_f32_e32 v200, v200
	v_exp_f32_e32 v201, v201
	v_exp_f32_e32 v202, v202
	v_exp_f32_e32 v203, v203
	v_exp_f32_e32 v204, v204
	v_exp_f32_e32 v205, v205
	v_pk_add_f32 v[198:199], v[198:199], s[42:43]
	v_pk_add_f32 v[200:201], v[200:201], s[42:43]
	v_pk_add_f32 v[202:203], v[202:203], s[42:43]
	v_pk_add_f32 v[204:205], v[204:205], s[42:43]
	v_rcp_f32_e32 v198, v198
	v_rcp_f32_e32 v199, v199
	v_rcp_f32_e32 v200, v200
	v_rcp_f32_e32 v201, v201
	v_rcp_f32_e32 v202, v202
	v_rcp_f32_e32 v203, v203
	v_rcp_f32_e32 v204, v204
	v_rcp_f32_e32 v205, v205
	v_pk_fma_f32 v[198:199], v[198:199], s[40:41], 0.5 op_sel_hi:[1,1,0]
	v_pk_fma_f32 v[200:201], v[200:201], s[40:41], 0.5 op_sel_hi:[1,1,0]
	v_pk_fma_f32 v[202:203], v[202:203], s[40:41], 0.5 op_sel_hi:[1,1,0]
	v_pk_fma_f32 v[204:205], v[204:205], s[40:41], 0.5 op_sel_hi:[1,1,0]
	v_cvt_u32_f32_e32 v198, v198
	v_cvt_u32_f32_e32 v199, v199
	v_cvt_u32_f32_e32 v200, v200
	v_cvt_u32_f32_e32 v201, v201
	v_cvt_u32_f32_e32 v202, v202
	v_cvt_u32_f32_e32 v203, v203
	v_cvt_u32_f32_e32 v204, v204
	v_cvt_u32_f32_e32 v205, v205
	v_lshl_or_b32 v198, v199, 8, v198
	v_lshl_or_b32 v200, v201, 8, v200
	v_lshl_or_b32 v202, v203, 8, v202
	v_lshl_or_b32 v204, v205, 8, v204
	v_lshl_or_b32 v208, v200, 16, v198
	v_lshl_or_b32 v209, v204, 16, v202
	s_nop 1
	v_permlane16_swap_b32 v206, v208
	v_permlane16_swap_b32 v207, v209
	global_store_dwordx4 v186, v[206:209], s[54:55]
	v_add_u32_e32 v187, 0x10000, v186
	v_pk_mul_f32 v[190:191], v[112:113], s[38:39]
	v_pk_mul_f32 v[192:193], v[114:115], s[38:39]
	v_pk_mul_f32 v[194:195], v[108:109], s[38:39]
	v_pk_mul_f32 v[196:197], v[110:111], s[38:39]
	v_exp_f32_e32 v190, v190
	v_exp_f32_e32 v191, v191
	v_exp_f32_e32 v192, v192
	v_exp_f32_e32 v193, v193
	v_exp_f32_e32 v194, v194
	v_exp_f32_e32 v195, v195
	v_exp_f32_e32 v196, v196
	v_exp_f32_e32 v197, v197
	v_pk_add_f32 v[190:191], v[190:191], s[42:43]
	v_pk_add_f32 v[192:193], v[192:193], s[42:43]
	v_pk_add_f32 v[194:195], v[194:195], s[42:43]
	v_pk_add_f32 v[196:197], v[196:197], s[42:43]
	v_rcp_f32_e32 v190, v190
	v_rcp_f32_e32 v191, v191
	v_rcp_f32_e32 v192, v192
	v_rcp_f32_e32 v193, v193
	v_rcp_f32_e32 v194, v194
	v_rcp_f32_e32 v195, v195
	v_rcp_f32_e32 v196, v196
	v_rcp_f32_e32 v197, v197
	v_pk_fma_f32 v[190:191], v[190:191], s[40:41], 0.5 op_sel_hi:[1,1,0]
	v_pk_fma_f32 v[192:193], v[192:193], s[40:41], 0.5 op_sel_hi:[1,1,0]
	v_pk_fma_f32 v[194:195], v[194:195], s[40:41], 0.5 op_sel_hi:[1,1,0]
	v_pk_fma_f32 v[196:197], v[196:197], s[40:41], 0.5 op_sel_hi:[1,1,0]
	v_cvt_u32_f32_e32 v190, v190
	v_cvt_u32_f32_e32 v191, v191
	v_cvt_u32_f32_e32 v192, v192
	v_cvt_u32_f32_e32 v193, v193
	v_cvt_u32_f32_e32 v194, v194
	v_cvt_u32_f32_e32 v195, v195
	v_cvt_u32_f32_e32 v196, v196
	v_cvt_u32_f32_e32 v197, v197
	v_lshl_or_b32 v190, v191, 8, v190
	v_lshl_or_b32 v192, v193, 8, v192
	v_lshl_or_b32 v194, v195, 8, v194
	v_lshl_or_b32 v196, v197, 8, v196
	v_lshl_or_b32 v218, v192, 16, v190
	v_lshl_or_b32 v219, v196, 16, v194
	v_pk_mul_f32 v[198:199], v[104:105], s[38:39]
	v_pk_mul_f32 v[200:201], v[106:107], s[38:39]
	v_pk_mul_f32 v[202:203], v[100:101], s[38:39]
	v_pk_mul_f32 v[204:205], v[102:103], s[38:39]
	v_exp_f32_e32 v198, v198
	v_exp_f32_e32 v199, v199
	v_exp_f32_e32 v200, v200
	v_exp_f32_e32 v201, v201
	v_exp_f32_e32 v202, v202
	v_exp_f32_e32 v203, v203
	v_exp_f32_e32 v204, v204
	v_exp_f32_e32 v205, v205
	v_pk_add_f32 v[198:199], v[198:199], s[42:43]
	v_pk_add_f32 v[200:201], v[200:201], s[42:43]
	v_pk_add_f32 v[202:203], v[202:203], s[42:43]
	v_pk_add_f32 v[204:205], v[204:205], s[42:43]
	v_rcp_f32_e32 v198, v198
	v_rcp_f32_e32 v199, v199
	v_rcp_f32_e32 v200, v200
; __device__ __forceinline__ float fast_rcp(float x) { return __builtin_amdgcn_rcpf(x); }
; __device__ __forceinline__ float fast_exp2(float x) { return __builtin_amdgcn_exp2f(x); }
; __device__ __forceinline__ float sigmoid_f(float x) { return fast_rcp(1.0f + fast_exp2(-1.4426950409f * x)); }
; __device__ __forceinline__ float gelu_tanh(float x) { const float t = x + 0.044715f * x * x * x; return x * fast_rcp(1.0f + fast_exp2(-2.3022081981f * t)); }
; __device__ __forceinline__ f32x4 gelu4(f32x4 v) { return (f32x4){gelu_tanh(v[0]), gelu_tanh(v[1]), gelu_tanh(v[2]), gelu_tanh(v[3])}; }
; __device__ __forceinline__ f32x4 sigm4(f32x4 v) { return (f32x4){sigmoid_f(v[0]), sigmoid_f(v[1]), sigmoid_f(v[2]), sigmoid_f(v[3])}; }
;     __device__ __forceinline__ void operator()(f32x4 (&acc)[2][2][4][2], const Unit& u, int wr, int wc, int fr, int fq) const {
;     ...
;                 for (int m = 0; m < 4; ++m) {
;                     const int row = row0 + ai * HALF + m * 16;
;                     float rstd = row_rstd(ss, row, fq); if (mode == 1) rstd *= 0.125f;
;                     bf16_t* rowp = base + (size_t)row * ldc + col0;
; #pragma unroll
;                     for (int bj = 0; bj < 2; ++bj) {
;                         f32x4 v0 = acc[ai][bj][m][0] * rstd, v1 = acc[ai][bj][m][1] * rstd;
;                         if (mode == 3) { u32x2 w; w.x = gate_q4(sigm4(v0)); w.y = gate_q4(sigm4(v1)); *(u32x2*)((unsigned char*)Gt + (size_t)row * 4096 + col0 + bj * 32) = w; continue; }
	v_rcp_f32_e32 v201, v201
	v_rcp_f32_e32 v202, v202
	v_rcp_f32_e32 v203, v203
	v_rcp_f32_e32 v204, v204
	v_rcp_f32_e32 v205, v205
	v_pk_fma_f32 v[198:199], v[198:199], s[40:41], 0.5 op_sel_hi:[1,1,0]
	v_pk_fma_f32 v[200:201], v[200:201], s[40:41], 0.5 op_sel_hi:[1,1,0]
	v_pk_fma_f32 v[202:203], v[202:203], s[40:41], 0.5 op_sel_hi:[1,1,0]
	v_pk_fma_f32 v[204:205], v[204:205], s[40:41], 0.5 op_sel_hi:[1,1,0]
	v_cvt_u32_f32_e32 v198, v198
	v_cvt_u32_f32_e32 v199, v199
	v_cvt_u32_f32_e32 v200, v200
	v_cvt_u32_f32_e32 v201, v201
	v_cvt_u32_f32_e32 v202, v202
	v_cvt_u32_f32_e32 v203, v203
	v_cvt_u32_f32_e32 v204, v204
	v_cvt_u32_f32_e32 v205, v205
	v_lshl_or_b32 v198, v199, 8, v198
	v_lshl_or_b32 v200, v201, 8, v200
	v_lshl_or_b32 v202, v203, 8, v202
	v_lshl_or_b32 v204, v205, 8, v204
	v_lshl_or_b32 v220, v200, 16, v198
	v_lshl_or_b32 v221, v204, 16, v202
	s_nop 1
	v_permlane16_swap_b32 v218, v220
	v_permlane16_swap_b32 v219, v221
	global_store_dwordx4 v187, v[218:221], s[54:55]
	v_add_u32_e32 v187, 0x20000, v186
	v_pk_mul_f32 v[190:191], v[96:97], s[38:39]
	v_pk_mul_f32 v[192:193], v[98:99], s[38:39]
	v_pk_mul_f32 v[194:195], v[92:93], s[38:39]
	v_pk_mul_f32 v[196:197], v[94:95], s[38:39]
	v_exp_f32_e32 v190, v190
	v_exp_f32_e32 v191, v191
	v_exp_f32_e32 v192, v192
	v_exp_f32_e32 v193, v193
	v_exp_f32_e32 v194, v194
	v_exp_f32_e32 v195, v195
	v_exp_f32_e32 v196, v196
	v_exp_f32_e32 v197, v197
	v_pk_add_f32 v[190:191], v[190:191], s[42:43]
	v_pk_add_f32 v[192:193], v[192:193], s[42:43]
	v_pk_add_f32 v[194:195], v[194:195], s[42:43]
	v_pk_add_f32 v[196:197], v[196:197], s[42:43]
	v_rcp_f32_e32 v190, v190
	v_rcp_f32_e32 v191, v191
	v_rcp_f32_e32 v192, v192
	v_rcp_f32_e32 v193, v193
	v_rcp_f32_e32 v194, v194
	v_rcp_f32_e32 v195, v195
	v_rcp_f32_e32 v196, v196
	v_rcp_f32_e32 v197, v197
	v_pk_fma_f32 v[190:191], v[190:191], s[40:41], 0.5 op_sel_hi:[1,1,0]
	v_pk_fma_f32 v[192:193], v[192:193], s[40:41], 0.5 op_sel_hi:[1,1,0]
	v_pk_fma_f32 v[194:195], v[194:195], s[40:41], 0.5 op_sel_hi:[1,1,0]
	v_pk_fma_f32 v[196:197], v[196:197], s[40:41], 0.5 op_sel_hi:[1,1,0]
	v_cvt_u32_f32_e32 v190, v190
	v_cvt_u32_f32_e32 v191, v191
	v_cvt_u32_f32_e32 v192, v192
	v_cvt_u32_f32_e32 v193, v193
	v_cvt_u32_f32_e32 v194, v194
	v_cvt_u32_f32_e32 v195, v195
	v_cvt_u32_f32_e32 v196, v196
	v_cvt_u32_f32_e32 v197, v197
	v_lshl_or_b32 v190, v191, 8, v190
	v_lshl_or_b32 v192, v193, 8, v192
	v_lshl_or_b32 v194, v195, 8, v194
	v_lshl_or_b32 v196, v197, 8, v196
	v_lshl_or_b32 v224, v192, 16, v190
	v_lshl_or_b32 v225, v196, 16, v194
	v_pk_mul_f32 v[198:199], v[88:89], s[38:39]
	v_pk_mul_f32 v[200:201], v[90:91], s[38:39]
	v_pk_mul_f32 v[202:203], v[84:85], s[38:39]
	v_pk_mul_f32 v[204:205], v[86:87], s[38:39]
	v_exp_f32_e32 v198, v198
	v_exp_f32_e32 v199, v199
	v_exp_f32_e32 v200, v200
	v_exp_f32_e32 v201, v201
	v_exp_f32_e32 v202, v202
	v_exp_f32_e32 v203, v203
	v_exp_f32_e32 v204, v204
	v_exp_f32_e32 v205, v205
	v_pk_add_f32 v[198:199], v[198:199], s[42:43]
	v_pk_add_f32 v[200:201], v[200:201], s[42:43]
	v_pk_add_f32 v[202:203], v[202:203], s[42:43]
	v_pk_add_f32 v[204:205], v[204:205], s[42:43]
	v_rcp_f32_e32 v198, v198
	v_rcp_f32_e32 v199, v199
	v_rcp_f32_e32 v200, v200
	v_rcp_f32_e32 v201, v201
	v_rcp_f32_e32 v202, v202
	v_rcp_f32_e32 v203, v203
	v_rcp_f32_e32 v204, v204
	v_rcp_f32_e32 v205, v205
	v_pk_fma_f32 v[198:199], v[198:199], s[40:41], 0.5 op_sel_hi:[1,1,0]
	v_pk_fma_f32 v[200:201], v[200:201], s[40:41], 0.5 op_sel_hi:[1,1,0]
	v_pk_fma_f32 v[202:203], v[202:203], s[40:41], 0.5 op_sel_hi:[1,1,0]
	v_pk_fma_f32 v[204:205], v[204:205], s[40:41], 0.5 op_sel_hi:[1,1,0]
	v_cvt_u32_f32_e32 v198, v198
	v_cvt_u32_f32_e32 v199, v199
	v_cvt_u32_f32_e32 v200, v200
	v_cvt_u32_f32_e32 v201, v201
	v_cvt_u32_f32_e32 v202, v202
	v_cvt_u32_f32_e32 v203, v203
	v_cvt_u32_f32_e32 v204, v204
	v_cvt_u32_f32_e32 v205, v205
	v_lshl_or_b32 v198, v199, 8, v198
	v_lshl_or_b32 v200, v201, 8, v200
	v_lshl_or_b32 v202, v203, 8, v202
	v_lshl_or_b32 v204, v205, 8, v204
	v_lshl_or_b32 v226, v200, 16, v198
	v_lshl_or_b32 v227, v204, 16, v202
	s_nop 1
	v_permlane16_swap_b32 v224, v226
	v_permlane16_swap_b32 v225, v227
	global_store_dwordx4 v187, v[224:227], s[54:55]
	v_add_u32_e32 v187, 0x30000, v186
	v_pk_mul_f32 v[190:191], v[80:81], s[38:39]
	v_pk_mul_f32 v[192:193], v[82:83], s[38:39]
	v_pk_mul_f32 v[194:195], v[76:77], s[38:39]
	v_pk_mul_f32 v[196:197], v[78:79], s[38:39]
	v_exp_f32_e32 v190, v190
	v_exp_f32_e32 v191, v191
	v_exp_f32_e32 v192, v192
	v_exp_f32_e32 v193, v193
	v_exp_f32_e32 v194, v194
	v_exp_f32_e32 v195, v195
	v_exp_f32_e32 v196, v196
	v_exp_f32_e32 v197, v197
	v_pk_add_f32 v[190:191], v[190:191], s[42:43]
	v_pk_add_f32 v[192:193], v[192:193], s[42:43]
	v_pk_add_f32 v[194:195], v[194:195], s[42:43]
	v_pk_add_f32 v[196:197], v[196:197], s[42:43]
	v_rcp_f32_e32 v190, v190
	v_rcp_f32_e32 v191, v191
	v_rcp_f32_e32 v192, v192
	v_rcp_f32_e32 v193, v193
	v_rcp_f32_e32 v194, v194
	v_rcp_f32_e32 v195, v195
	v_rcp_f32_e32 v196, v196
	v_rcp_f32_e32 v197, v197
	v_pk_fma_f32 v[190:191], v[190:191], s[40:41], 0.5 op_sel_hi:[1,1,0]
	v_pk_fma_f32 v[192:193], v[192:193], s[40:41], 0.5 op_sel_hi:[1,1,0]
	v_pk_fma_f32 v[194:195], v[194:195], s[40:41], 0.5 op_sel_hi:[1,1,0]
	v_pk_fma_f32 v[196:197], v[196:197], s[40:41], 0.5 op_sel_hi:[1,1,0]
	v_cvt_u32_f32_e32 v190, v190
	v_cvt_u32_f32_e32 v191, v191
	v_cvt_u32_f32_e32 v192, v192
	v_cvt_u32_f32_e32 v193, v193
	v_cvt_u32_f32_e32 v194, v194
	v_cvt_u32_f32_e32 v195, v195
	v_cvt_u32_f32_e32 v196, v196
	v_cvt_u32_f32_e32 v197, v197
	v_lshl_or_b32 v190, v191, 8, v190
	v_lshl_or_b32 v192, v193, 8, v192
	v_lshl_or_b32 v194, v195, 8, v194
; __device__ __forceinline__ float fast_rcp(float x) { return __builtin_amdgcn_rcpf(x); }
; __device__ __forceinline__ float fast_exp2(float x) { return __builtin_amdgcn_exp2f(x); }
; __device__ __forceinline__ float sigmoid_f(float x) { return fast_rcp(1.0f + fast_exp2(-1.4426950409f * x)); }
; __device__ __forceinline__ float gelu_tanh(float x) { const float t = x + 0.044715f * x * x * x; return x * fast_rcp(1.0f + fast_exp2(-2.3022081981f * t)); }
; __device__ __forceinline__ f32x4 gelu4(f32x4 v) { return (f32x4){gelu_tanh(v[0]), gelu_tanh(v[1]), gelu_tanh(v[2]), gelu_tanh(v[3])}; }
; __device__ __forceinline__ f32x4 sigm4(f32x4 v) { return (f32x4){sigmoid_f(v[0]), sigmoid_f(v[1]), sigmoid_f(v[2]), sigmoid_f(v[3])}; }
;     __device__ __forceinline__ void operator()(f32x4 (&acc)[2][2][4][2], const Unit& u, int wr, int wc, int fr, int fq) const {
;     ...
;                 for (int m = 0; m < 4; ++m) {
;                     const int row = row0 + ai * HALF + m * 16;
;                     float rstd = row_rstd(ss, row, fq); if (mode == 1) rstd *= 0.125f;
;                     bf16_t* rowp = base + (size_t)row * ldc + col0;
; #pragma unroll
;                     for (int bj = 0; bj < 2; ++bj) {
;                         f32x4 v0 = acc[ai][bj][m][0] * rstd, v1 = acc[ai][bj][m][1] * rstd;
;                         if (mode == 3) { u32x2 w; w.x = gate_q4(sigm4(v0)); w.y = gate_q4(sigm4(v1)); *(u32x2*)((unsigned char*)Gt + (size_t)row * 4096 + col0 + bj * 32) = w; continue; }
	v_lshl_or_b32 v196, v197, 8, v196
	v_lshl_or_b32 v228, v192, 16, v190
	v_lshl_or_b32 v229, v196, 16, v194
	v_pk_mul_f32 v[198:199], v[72:73], s[38:39]
	v_pk_mul_f32 v[200:201], v[74:75], s[38:39]
	v_pk_mul_f32 v[202:203], v[68:69], s[38:39]
	v_pk_mul_f32 v[204:205], v[70:71], s[38:39]
	v_exp_f32_e32 v198, v198
	v_exp_f32_e32 v199, v199
	v_exp_f32_e32 v200, v200
	v_exp_f32_e32 v201, v201
	v_exp_f32_e32 v202, v202
	v_exp_f32_e32 v203, v203
	v_exp_f32_e32 v204, v204
	v_exp_f32_e32 v205, v205
	v_pk_add_f32 v[198:199], v[198:199], s[42:43]
	v_pk_add_f32 v[200:201], v[200:201], s[42:43]
	v_pk_add_f32 v[202:203], v[202:203], s[42:43]
	v_pk_add_f32 v[204:205], v[204:205], s[42:43]
	v_rcp_f32_e32 v198, v198
	v_rcp_f32_e32 v199, v199
	v_rcp_f32_e32 v200, v200
	v_rcp_f32_e32 v201, v201
	v_rcp_f32_e32 v202, v202
	v_rcp_f32_e32 v203, v203
	v_rcp_f32_e32 v204, v204
	v_rcp_f32_e32 v205, v205
	v_pk_fma_f32 v[198:199], v[198:199], s[40:41], 0.5 op_sel_hi:[1,1,0]
	v_pk_fma_f32 v[200:201], v[200:201], s[40:41], 0.5 op_sel_hi:[1,1,0]
	v_pk_fma_f32 v[202:203], v[202:203], s[40:41], 0.5 op_sel_hi:[1,1,0]
	v_pk_fma_f32 v[204:205], v[204:205], s[40:41], 0.5 op_sel_hi:[1,1,0]
	v_cvt_u32_f32_e32 v198, v198
	v_cvt_u32_f32_e32 v199, v199
	v_cvt_u32_f32_e32 v200, v200
	v_cvt_u32_f32_e32 v201, v201
	v_cvt_u32_f32_e32 v202, v202
	v_cvt_u32_f32_e32 v203, v203
	v_cvt_u32_f32_e32 v204, v204
	v_cvt_u32_f32_e32 v205, v205
	v_lshl_or_b32 v198, v199, 8, v198
	v_lshl_or_b32 v200, v201, 8, v200
	v_lshl_or_b32 v202, v203, 8, v202
	v_lshl_or_b32 v204, v205, 8, v204
	v_lshl_or_b32 v230, v200, 16, v198
	v_lshl_or_b32 v231, v204, 16, v202
	s_nop 1
	v_permlane16_swap_b32 v228, v230
	v_permlane16_swap_b32 v229, v231
	global_store_dwordx4 v187, v[228:231], s[54:55]
	v_add_u32_e32 v187, 0x80000, v186
	v_pk_mul_f32 v[190:191], v[64:65], s[38:39]
	v_pk_mul_f32 v[192:193], v[66:67], s[38:39]
	v_pk_mul_f32 v[194:195], v[60:61], s[38:39]
	v_pk_mul_f32 v[196:197], v[62:63], s[38:39]
	v_exp_f32_e32 v190, v190
	v_exp_f32_e32 v191, v191
	v_exp_f32_e32 v192, v192
	v_exp_f32_e32 v193, v193
	v_exp_f32_e32 v194, v194
	v_exp_f32_e32 v195, v195
	v_exp_f32_e32 v196, v196
	v_exp_f32_e32 v197, v197
	v_pk_add_f32 v[190:191], v[190:191], s[42:43]
	v_pk_add_f32 v[192:193], v[192:193], s[42:43]
	v_pk_add_f32 v[194:195], v[194:195], s[42:43]
	v_pk_add_f32 v[196:197], v[196:197], s[42:43]
	v_rcp_f32_e32 v190, v190
	v_rcp_f32_e32 v191, v191
	v_rcp_f32_e32 v192, v192
	v_rcp_f32_e32 v193, v193
	v_rcp_f32_e32 v194, v194
	v_rcp_f32_e32 v195, v195
	v_rcp_f32_e32 v196, v196
	v_rcp_f32_e32 v197, v197
	v_pk_fma_f32 v[190:191], v[190:191], s[40:41], 0.5 op_sel_hi:[1,1,0]
	v_pk_fma_f32 v[192:193], v[192:193], s[40:41], 0.5 op_sel_hi:[1,1,0]
	v_pk_fma_f32 v[194:195], v[194:195], s[40:41], 0.5 op_sel_hi:[1,1,0]
	v_pk_fma_f32 v[196:197], v[196:197], s[40:41], 0.5 op_sel_hi:[1,1,0]
	v_cvt_u32_f32_e32 v190, v190
	v_cvt_u32_f32_e32 v191, v191
	v_cvt_u32_f32_e32 v192, v192
	v_cvt_u32_f32_e32 v193, v193
	v_cvt_u32_f32_e32 v194, v194
	v_cvt_u32_f32_e32 v195, v195
	v_cvt_u32_f32_e32 v196, v196
	v_cvt_u32_f32_e32 v197, v197
	v_lshl_or_b32 v190, v191, 8, v190
	v_lshl_or_b32 v192, v193, 8, v192
	v_lshl_or_b32 v194, v195, 8, v194
	v_lshl_or_b32 v196, v197, 8, v196
	v_lshl_or_b32 v206, v192, 16, v190
	v_lshl_or_b32 v207, v196, 16, v194
	v_pk_mul_f32 v[198:199], v[56:57], s[38:39]
	v_pk_mul_f32 v[200:201], v[58:59], s[38:39]
	v_pk_mul_f32 v[202:203], v[52:53], s[38:39]
	v_pk_mul_f32 v[204:205], v[54:55], s[38:39]
	v_exp_f32_e32 v198, v198
	v_exp_f32_e32 v199, v199
	v_exp_f32_e32 v200, v200
	v_exp_f32_e32 v201, v201
	v_exp_f32_e32 v202, v202
	v_exp_f32_e32 v203, v203
	v_exp_f32_e32 v204, v204
	v_exp_f32_e32 v205, v205
	v_pk_add_f32 v[198:199], v[198:199], s[42:43]
	v_pk_add_f32 v[200:201], v[200:201], s[42:43]
	v_pk_add_f32 v[202:203], v[202:203], s[42:43]
	v_pk_add_f32 v[204:205], v[204:205], s[42:43]
	v_rcp_f32_e32 v198, v198
	v_rcp_f32_e32 v199, v199
	v_rcp_f32_e32 v200, v200
	v_rcp_f32_e32 v201, v201
	v_rcp_f32_e32 v202, v202
	v_rcp_f32_e32 v203, v203
	v_rcp_f32_e32 v204, v204
	v_rcp_f32_e32 v205, v205
	v_pk_fma_f32 v[198:199], v[198:199], s[40:41], 0.5 op_sel_hi:[1,1,0]
	v_pk_fma_f32 v[200:201], v[200:201], s[40:41], 0.5 op_sel_hi:[1,1,0]
	v_pk_fma_f32 v[202:203], v[202:203], s[40:41], 0.5 op_sel_hi:[1,1,0]
	v_pk_fma_f32 v[204:205], v[204:205], s[40:41], 0.5 op_sel_hi:[1,1,0]
	v_cvt_u32_f32_e32 v198, v198
	v_cvt_u32_f32_e32 v199, v199
	v_cvt_u32_f32_e32 v200, v200
	v_cvt_u32_f32_e32 v201, v201
	v_cvt_u32_f32_e32 v202, v202
	v_cvt_u32_f32_e32 v203, v203
	v_cvt_u32_f32_e32 v204, v204
	v_cvt_u32_f32_e32 v205, v205
	v_lshl_or_b32 v198, v199, 8, v198
	v_lshl_or_b32 v200, v201, 8, v200
	v_lshl_or_b32 v202, v203, 8, v202
	v_lshl_or_b32 v204, v205, 8, v204
	v_lshl_or_b32 v208, v200, 16, v198
	v_lshl_or_b32 v209, v204, 16, v202
	s_nop 1
	v_permlane16_swap_b32 v206, v208
	v_permlane16_swap_b32 v207, v209
	global_store_dwordx4 v187, v[206:209], s[54:55]
	v_add_u32_e32 v187, 0x90000, v186
	v_pk_mul_f32 v[190:191], v[48:49], s[38:39]
	v_pk_mul_f32 v[192:193], v[50:51], s[38:39]
	v_pk_mul_f32 v[194:195], v[44:45], s[38:39]
	v_pk_mul_f32 v[196:197], v[46:47], s[38:39]
	v_exp_f32_e32 v190, v190
	v_exp_f32_e32 v191, v191
	v_exp_f32_e32 v192, v192
	v_exp_f32_e32 v193, v193
	v_exp_f32_e32 v194, v194
	v_exp_f32_e32 v195, v195
	v_exp_f32_e32 v196, v196
	v_exp_f32_e32 v197, v197
	v_pk_add_f32 v[190:191], v[190:191], s[42:43]
	v_pk_add_f32 v[192:193], v[192:193], s[42:43]
	v_pk_add_f32 v[194:195], v[194:195], s[42:43]
	v_pk_add_f32 v[196:197], v[196:197], s[42:43]
	v_rcp_f32_e32 v190, v190
	v_rcp_f32_e32 v191, v191
	v_rcp_f32_e32 v192, v192
; __device__ __forceinline__ float fast_rcp(float x) { return __builtin_amdgcn_rcpf(x); }
; __device__ __forceinline__ float fast_exp2(float x) { return __builtin_amdgcn_exp2f(x); }
; __device__ __forceinline__ float sigmoid_f(float x) { return fast_rcp(1.0f + fast_exp2(-1.4426950409f * x)); }
; __device__ __forceinline__ float gelu_tanh(float x) { const float t = x + 0.044715f * x * x * x; return x * fast_rcp(1.0f + fast_exp2(-2.3022081981f * t)); }
; __device__ __forceinline__ f32x4 gelu4(f32x4 v) { return (f32x4){gelu_tanh(v[0]), gelu_tanh(v[1]), gelu_tanh(v[2]), gelu_tanh(v[3])}; }
; __device__ __forceinline__ f32x4 sigm4(f32x4 v) { return (f32x4){sigmoid_f(v[0]), sigmoid_f(v[1]), sigmoid_f(v[2]), sigmoid_f(v[3])}; }
;     __device__ __forceinline__ void operator()(f32x4 (&acc)[2][2][4][2], const Unit& u, int wr, int wc, int fr, int fq) const {
;     ...
;                 for (int m = 0; m < 4; ++m) {
;                     const int row = row0 + ai * HALF + m * 16;
;                     float rstd = row_rstd(ss, row, fq); if (mode == 1) rstd *= 0.125f;
;                     bf16_t* rowp = base + (size_t)row * ldc + col0;
; #pragma unroll
;                     for (int bj = 0; bj < 2; ++bj) {
;                         f32x4 v0 = acc[ai][bj][m][0] * rstd, v1 = acc[ai][bj][m][1] * rstd;
;                         if (mode == 3) { u32x2 w; w.x = gate_q4(sigm4(v0)); w.y = gate_q4(sigm4(v1)); *(u32x2*)((unsigned char*)Gt + (size_t)row * 4096 + col0 + bj * 32) = w; continue; }
	v_rcp_f32_e32 v193, v193
	v_rcp_f32_e32 v194, v194
	v_rcp_f32_e32 v195, v195
	v_rcp_f32_e32 v196, v196
	v_rcp_f32_e32 v197, v197
	v_pk_fma_f32 v[190:191], v[190:191], s[40:41], 0.5 op_sel_hi:[1,1,0]
	v_pk_fma_f32 v[192:193], v[192:193], s[40:41], 0.5 op_sel_hi:[1,1,0]
	v_pk_fma_f32 v[194:195], v[194:195], s[40:41], 0.5 op_sel_hi:[1,1,0]
	v_pk_fma_f32 v[196:197], v[196:197], s[40:41], 0.5 op_sel_hi:[1,1,0]
	v_cvt_u32_f32_e32 v190, v190
	v_cvt_u32_f32_e32 v191, v191
	v_cvt_u32_f32_e32 v192, v192
	v_cvt_u32_f32_e32 v193, v193
	v_cvt_u32_f32_e32 v194, v194
	v_cvt_u32_f32_e32 v195, v195
	v_cvt_u32_f32_e32 v196, v196
	v_cvt_u32_f32_e32 v197, v197
	v_lshl_or_b32 v190, v191, 8, v190
	v_lshl_or_b32 v192, v193, 8, v192
	v_lshl_or_b32 v194, v195, 8, v194
	v_lshl_or_b32 v196, v197, 8, v196
	v_lshl_or_b32 v218, v192, 16, v190
	v_lshl_or_b32 v219, v196, 16, v194
	v_pk_mul_f32 v[198:199], v[40:41], s[38:39]
	v_pk_mul_f32 v[200:201], v[42:43], s[38:39]
	v_pk_mul_f32 v[202:203], v[36:37], s[38:39]
	v_pk_mul_f32 v[204:205], v[38:39], s[38:39]
	v_exp_f32_e32 v198, v198
	v_exp_f32_e32 v199, v199
	v_exp_f32_e32 v200, v200
	v_exp_f32_e32 v201, v201
	v_exp_f32_e32 v202, v202
	v_exp_f32_e32 v203, v203
	v_exp_f32_e32 v204, v204
	v_exp_f32_e32 v205, v205
	v_pk_add_f32 v[198:199], v[198:199], s[42:43]
	v_pk_add_f32 v[200:201], v[200:201], s[42:43]
	v_pk_add_f32 v[202:203], v[202:203], s[42:43]
	v_pk_add_f32 v[204:205], v[204:205], s[42:43]
	v_rcp_f32_e32 v198, v198
	v_rcp_f32_e32 v199, v199
	v_rcp_f32_e32 v200, v200
	v_rcp_f32_e32 v201, v201
	v_rcp_f32_e32 v202, v202
	v_rcp_f32_e32 v203, v203
	v_rcp_f32_e32 v204, v204
	v_rcp_f32_e32 v205, v205
	v_pk_fma_f32 v[198:199], v[198:199], s[40:41], 0.5 op_sel_hi:[1,1,0]
	v_pk_fma_f32 v[200:201], v[200:201], s[40:41], 0.5 op_sel_hi:[1,1,0]
	v_pk_fma_f32 v[202:203], v[202:203], s[40:41], 0.5 op_sel_hi:[1,1,0]
	v_pk_fma_f32 v[204:205], v[204:205], s[40:41], 0.5 op_sel_hi:[1,1,0]
	v_cvt_u32_f32_e32 v198, v198
	v_cvt_u32_f32_e32 v199, v199
	v_cvt_u32_f32_e32 v200, v200
	v_cvt_u32_f32_e32 v201, v201
	v_cvt_u32_f32_e32 v202, v202
	v_cvt_u32_f32_e32 v203, v203
	v_cvt_u32_f32_e32 v204, v204
	v_cvt_u32_f32_e32 v205, v205
	v_lshl_or_b32 v198, v199, 8, v198
	v_lshl_or_b32 v200, v201, 8, v200
	v_lshl_or_b32 v202, v203, 8, v202
	v_lshl_or_b32 v204, v205, 8, v204
	v_lshl_or_b32 v220, v200, 16, v198
	v_lshl_or_b32 v221, v204, 16, v202
	s_nop 1
	v_permlane16_swap_b32 v218, v220
	v_permlane16_swap_b32 v219, v221
	global_store_dwordx4 v187, v[218:221], s[54:55]
	v_add_u32_e32 v187, 0xa0000, v186
	v_pk_mul_f32 v[190:191], v[32:33], s[38:39]
	v_pk_mul_f32 v[192:193], v[34:35], s[38:39]
	v_pk_mul_f32 v[194:195], v[28:29], s[38:39]
	v_pk_mul_f32 v[196:197], v[30:31], s[38:39]
	v_exp_f32_e32 v190, v190
	v_exp_f32_e32 v191, v191
	v_exp_f32_e32 v192, v192
	v_exp_f32_e32 v193, v193
	v_exp_f32_e32 v194, v194
	v_exp_f32_e32 v195, v195
	v_exp_f32_e32 v196, v196
	v_exp_f32_e32 v197, v197
	v_pk_add_f32 v[190:191], v[190:191], s[42:43]
	v_pk_add_f32 v[192:193], v[192:193], s[42:43]
	v_pk_add_f32 v[194:195], v[194:195], s[42:43]
	v_pk_add_f32 v[196:197], v[196:197], s[42:43]
	v_rcp_f32_e32 v190, v190
	v_rcp_f32_e32 v191, v191
	v_rcp_f32_e32 v192, v192
	v_rcp_f32_e32 v193, v193
	v_rcp_f32_e32 v194, v194
	v_rcp_f32_e32 v195, v195
	v_rcp_f32_e32 v196, v196
	v_rcp_f32_e32 v197, v197
	v_pk_fma_f32 v[190:191], v[190:191], s[40:41], 0.5 op_sel_hi:[1,1,0]
	v_pk_fma_f32 v[192:193], v[192:193], s[40:41], 0.5 op_sel_hi:[1,1,0]
	v_pk_fma_f32 v[194:195], v[194:195], s[40:41], 0.5 op_sel_hi:[1,1,0]
	v_pk_fma_f32 v[196:197], v[196:197], s[40:41], 0.5 op_sel_hi:[1,1,0]
	v_cvt_u32_f32_e32 v190, v190
	v_cvt_u32_f32_e32 v191, v191
	v_cvt_u32_f32_e32 v192, v192
	v_cvt_u32_f32_e32 v193, v193
	v_cvt_u32_f32_e32 v194, v194
	v_cvt_u32_f32_e32 v195, v195
	v_cvt_u32_f32_e32 v196, v196
	v_cvt_u32_f32_e32 v197, v197
	v_lshl_or_b32 v190, v191, 8, v190
	v_lshl_or_b32 v192, v193, 8, v192
	v_lshl_or_b32 v194, v195, 8, v194
	v_lshl_or_b32 v196, v197, 8, v196
	v_lshl_or_b32 v224, v192, 16, v190
	v_lshl_or_b32 v225, v196, 16, v194
	v_pk_mul_f32 v[198:199], v[24:25], s[38:39]
	v_pk_mul_f32 v[200:201], v[26:27], s[38:39]
	v_pk_mul_f32 v[202:203], v[20:21], s[38:39]
	v_pk_mul_f32 v[204:205], v[22:23], s[38:39]
	v_exp_f32_e32 v198, v198
	v_exp_f32_e32 v199, v199
	v_exp_f32_e32 v200, v200
	v_exp_f32_e32 v201, v201
	v_exp_f32_e32 v202, v202
	v_exp_f32_e32 v203, v203
	v_exp_f32_e32 v204, v204
	v_exp_f32_e32 v205, v205
; __device__ __forceinline__ float fast_rcp(float x) { return __builtin_amdgcn_rcpf(x); }
; __device__ __forceinline__ float fast_exp2(float x) { return __builtin_amdgcn_exp2f(x); }
; __device__ __forceinline__ float sigmoid_f(float x) { return fast_rcp(1.0f + fast_exp2(-1.4426950409f * x)); }
; __device__ __forceinline__ float gelu_tanh(float x) { const float t = x + 0.044715f * x * x * x; return x * fast_rcp(1.0f + fast_exp2(-2.3022081981f * t)); }
; __device__ __forceinline__ f32x4 gelu4(f32x4 v) { return (f32x4){gelu_tanh(v[0]), gelu_tanh(v[1]), gelu_tanh(v[2]), gelu_tanh(v[3])}; }
; __device__ __forceinline__ f32x4 sigm4(f32x4 v) { return (f32x4){sigmoid_f(v[0]), sigmoid_f(v[1]), sigmoid_f(v[2]), sigmoid_f(v[3])}; }
;     __device__ __forceinline__ void operator()(f32x4 (&acc)[2][2][4][2], const Unit& u, int wr, int wc, int fr, int fq) const {
;     ...
;                 for (int m = 0; m < 4; ++m) {
;                     const int row = row0 + ai * HALF + m * 16;
;                     float rstd = row_rstd(ss, row, fq); if (mode == 1) rstd *= 0.125f;
;                     bf16_t* rowp = base + (size_t)row * ldc + col0;
; #pragma unroll
;                     for (int bj = 0; bj < 2; ++bj) {
;                         f32x4 v0 = acc[ai][bj][m][0] * rstd, v1 = acc[ai][bj][m][1] * rstd;
;                         if (mode == 3) { u32x2 w; w.x = gate_q4(sigm4(v0)); w.y = gate_q4(sigm4(v1)); *(u32x2*)((unsigned char*)Gt + (size_t)row * 4096 + col0 + bj * 32) = w; continue; }
	v_pk_add_f32 v[198:199], v[198:199], s[42:43]
	v_pk_add_f32 v[200:201], v[200:201], s[42:43]
	v_pk_add_f32 v[202:203], v[202:203], s[42:43]
	v_pk_add_f32 v[204:205], v[204:205], s[42:43]
	v_rcp_f32_e32 v198, v198
	v_rcp_f32_e32 v199, v199
	v_rcp_f32_e32 v200, v200
	v_rcp_f32_e32 v201, v201
	v_rcp_f32_e32 v202, v202
	v_rcp_f32_e32 v203, v203
	v_rcp_f32_e32 v204, v204
	v_rcp_f32_e32 v205, v205
	v_pk_fma_f32 v[198:199], v[198:199], s[40:41], 0.5 op_sel_hi:[1,1,0]
	v_pk_fma_f32 v[200:201], v[200:201], s[40:41], 0.5 op_sel_hi:[1,1,0]
	v_pk_fma_f32 v[202:203], v[202:203], s[40:41], 0.5 op_sel_hi:[1,1,0]
	v_pk_fma_f32 v[204:205], v[204:205], s[40:41], 0.5 op_sel_hi:[1,1,0]
	v_cvt_u32_f32_e32 v198, v198
	v_cvt_u32_f32_e32 v199, v199
	v_cvt_u32_f32_e32 v200, v200
	v_cvt_u32_f32_e32 v201, v201
	v_cvt_u32_f32_e32 v202, v202
	v_cvt_u32_f32_e32 v203, v203
	v_cvt_u32_f32_e32 v204, v204
	v_cvt_u32_f32_e32 v205, v205
	v_lshl_or_b32 v198, v199, 8, v198
	v_lshl_or_b32 v200, v201, 8, v200
	v_lshl_or_b32 v202, v203, 8, v202
	v_lshl_or_b32 v204, v205, 8, v204
	v_lshl_or_b32 v226, v200, 16, v198
	v_lshl_or_b32 v227, v204, 16, v202
	s_nop 1
	v_permlane16_swap_b32 v224, v226
	v_permlane16_swap_b32 v225, v227
	global_store_dwordx4 v187, v[224:227], s[54:55]
	v_add_u32_e32 v187, 0xb0000, v186
	v_pk_mul_f32 v[190:191], v[16:17], s[38:39]
	v_pk_mul_f32 v[192:193], v[18:19], s[38:39]
	v_pk_mul_f32 v[194:195], v[12:13], s[38:39]
	v_pk_mul_f32 v[196:197], v[14:15], s[38:39]
	v_exp_f32_e32 v190, v190
	v_exp_f32_e32 v191, v191
	v_exp_f32_e32 v192, v192
	v_exp_f32_e32 v193, v193
	v_exp_f32_e32 v194, v194
	v_exp_f32_e32 v195, v195
	v_exp_f32_e32 v196, v196
	v_exp_f32_e32 v197, v197
	v_pk_add_f32 v[190:191], v[190:191], s[42:43]
	v_pk_add_f32 v[192:193], v[192:193], s[42:43]
	v_pk_add_f32 v[194:195], v[194:195], s[42:43]
	v_pk_add_f32 v[196:197], v[196:197], s[42:43]
	v_rcp_f32_e32 v190, v190
	v_rcp_f32_e32 v191, v191
	v_rcp_f32_e32 v192, v192
	v_rcp_f32_e32 v193, v193
	v_rcp_f32_e32 v194, v194
	v_rcp_f32_e32 v195, v195
	v_rcp_f32_e32 v196, v196
	v_rcp_f32_e32 v197, v197
	v_pk_fma_f32 v[190:191], v[190:191], s[40:41], 0.5 op_sel_hi:[1,1,0]
	v_pk_fma_f32 v[192:193], v[192:193], s[40:41], 0.5 op_sel_hi:[1,1,0]
	v_pk_fma_f32 v[194:195], v[194:195], s[40:41], 0.5 op_sel_hi:[1,1,0]
	v_pk_fma_f32 v[196:197], v[196:197], s[40:41], 0.5 op_sel_hi:[1,1,0]
	v_cvt_u32_f32_e32 v190, v190
	v_cvt_u32_f32_e32 v191, v191
	v_cvt_u32_f32_e32 v192, v192
	v_cvt_u32_f32_e32 v193, v193
	v_cvt_u32_f32_e32 v194, v194
	v_cvt_u32_f32_e32 v195, v195
	v_cvt_u32_f32_e32 v196, v196
	v_cvt_u32_f32_e32 v197, v197
	v_lshl_or_b32 v190, v191, 8, v190
	v_lshl_or_b32 v192, v193, 8, v192
	v_lshl_or_b32 v194, v195, 8, v194
	v_lshl_or_b32 v196, v197, 8, v196
	v_lshl_or_b32 v228, v192, 16, v190
	v_lshl_or_b32 v229, v196, 16, v194
	v_pk_mul_f32 v[198:199], v[8:9], s[38:39]
	v_pk_mul_f32 v[200:201], v[10:11], s[38:39]
	v_pk_mul_f32 v[202:203], v[4:5], s[38:39]
	v_pk_mul_f32 v[204:205], v[6:7], s[38:39]
	v_exp_f32_e32 v198, v198
	v_exp_f32_e32 v199, v199
	v_exp_f32_e32 v200, v200
	v_exp_f32_e32 v201, v201
	v_exp_f32_e32 v202, v202
	v_exp_f32_e32 v203, v203
	v_exp_f32_e32 v204, v204
	v_exp_f32_e32 v205, v205
	v_pk_add_f32 v[198:199], v[198:199], s[42:43]
	v_pk_add_f32 v[200:201], v[200:201], s[42:43]
	v_pk_add_f32 v[202:203], v[202:203], s[42:43]
	v_pk_add_f32 v[204:205], v[204:205], s[42:43]
	v_rcp_f32_e32 v198, v198
	v_rcp_f32_e32 v199, v199
	v_rcp_f32_e32 v200, v200
	v_rcp_f32_e32 v201, v201
	v_rcp_f32_e32 v202, v202
	v_rcp_f32_e32 v203, v203
	v_rcp_f32_e32 v204, v204
	v_rcp_f32_e32 v205, v205
	v_pk_fma_f32 v[198:199], v[198:199], s[40:41], 0.5 op_sel_hi:[1,1,0]
	v_pk_fma_f32 v[200:201], v[200:201], s[40:41], 0.5 op_sel_hi:[1,1,0]
	v_pk_fma_f32 v[202:203], v[202:203], s[40:41], 0.5 op_sel_hi:[1,1,0]
	v_pk_fma_f32 v[204:205], v[204:205], s[40:41], 0.5 op_sel_hi:[1,1,0]
	v_cvt_u32_f32_e32 v198, v198
	v_cvt_u32_f32_e32 v199, v199
	v_cvt_u32_f32_e32 v200, v200
	v_cvt_u32_f32_e32 v201, v201
	v_cvt_u32_f32_e32 v202, v202
	v_cvt_u32_f32_e32 v203, v203
	v_cvt_u32_f32_e32 v204, v204
	v_cvt_u32_f32_e32 v205, v205
	v_lshl_or_b32 v198, v199, 8, v198
	v_lshl_or_b32 v200, v201, 8, v200
	v_lshl_or_b32 v202, v203, 8, v202
	v_lshl_or_b32 v204, v205, 8, v204
	v_lshl_or_b32 v230, v200, 16, v198
	v_lshl_or_b32 v231, v204, 16, v202
	s_nop 1
	v_permlane16_swap_b32 v228, v230
	v_permlane16_swap_b32 v229, v231
	global_store_dwordx4 v187, v[228:231], s[54:55]

; __device__ __forceinline__ unsigned cvt_pk_bf16(float lo, float hi) { unsigned r; asm volatile("v_cvt_pk_bf16_f32 %0, %1, %2" : "=v"(r) : "v"(lo), "v"(hi)); return r; }
; __device__ __forceinline__ float bf_lo(unsigned w) { return __uint_as_float(w << 16); }
; __device__ __forceinline__ float bf_hi(unsigned w) { return __uint_as_float(w & 0xffff0000u); }
; __device__ __forceinline__ float fast_exp2(float x) { return __builtin_amdgcn_exp2f(x); }
; __device__ __forceinline__ void attn_phase(const bf16_t* Q, const bf16_t* Kb, const bf16_t* VTa, const float* rpb, bf16_t* Y, LAS unsigned char* lds, int bx, int G, int tid, int wave, int lane) {
;     ...
;             if (hf == 0) {
;                 const float m1 = ml[0], l1 = ml[1];
;                 const float m = fmaxf(mx, m1), sc0 = fast_exp2((mx - m) * 1.4426950409f), sc1 = fast_exp2((m1 - m) * 1.4426950409f);
;                 const float inv = 1.0f / (l * sc0 + l1 * sc1);
;                 bf16_t* yp = Y + (size_t)(r * 64 + c) * 2048 + 1024 + h * 64 + 4 * fq;
; #pragma unroll
;                 for (int dt = 0; dt < 4; ++dt) { const u32x2 pw = ol[dt]; const f32x4 o1 = {bf_lo(pw.x), bf_hi(pw.x), bf_lo(pw.y), bf_hi(pw.y)}; const f32x4 v = (o[dt] * sc0 + o1 * sc1) * inv;
;                     u32x2 w; w.x = cvt_pk_bf16(v[0], v[1]); w.y = cvt_pk_bf16(v[2], v[3]); *(u32x2*)(yp + 16 * dt) = w; }
;             }
.LBB0_459:
	s_waitcnt lgkmcnt(0)
	s_barrier
	v_cndmask_b32_e64 v26, 0, 1, s[12:13]
	v_cmp_ne_u32_e64 s[56:57], 1, v26
	s_andn2_b64 vcc, exec, s[12:13]
	s_cbranch_vccnz .LBB0_461
	v_add_u32_e32 v26, 0, v57
	v_add_u32_e32 v26, 0x20800, v26
	ds_read_b64 v[26:27], v26
	v_add_u32_e32 v28, 0, v59
	v_add_u32_e32 v63, 0x21000, v28
	v_max_f32_e32 v35, v32, v32
	ds_read_b64 v[28:29], v63
	ds_read_b64 v[222:223], v63 offset:8
	ds_read_b64 v[224:225], v63 offset:16
	ds_read_b64 v[226:227], v63 offset:24
	s_waitcnt lgkmcnt(3)
	v_max_f32_e32 v36, v26, v26
	v_max_f32_e32 v35, v35, v36
	v_sub_f32_e32 v32, v32, v35
	v_sub_f32_e32 v26, v26, v35
	v_mul_f32_e32 v32, 0x3fb8aa3b, v32
	v_mul_f32_e32 v26, 0x3fb8aa3b, v26
	v_exp_f32_e32 v36, v32
	v_exp_f32_e32 v37, v26
	v_mov_b32_e32 v26, v33
	v_ashrrev_i32_e32 v99, 31, v98
	v_pk_mul_f32 v[26:27], v[26:27], v[36:37]
	s_nop 0
	v_add_f32_e32 v26, v26, v27
	v_div_scale_f32 v27, vcc, v26, v26, 1.0
	v_rcp_f32_e32 v32, v27
	v_mov_b32_e32 v100, v37
	v_fma_f32 v33, -v27, v32, 1.0
	v_fmac_f32_e32 v32, v33, v32
	v_div_scale_f32 v33, vcc, 1.0, v26, 1.0
	v_mul_f32_e32 v35, v33, v32
	v_fma_f32 v65, -v27, v35, v33
	v_fmac_f32_e32 v35, v65, v32
	v_fma_f32 v27, -v27, v35, v33
	v_div_fmas_f32 v27, v27, v32, v35
	v_lshlrev_b32_e32 v32, 16, v28
	v_and_b32_e32 v33, 0xffff0000, v28
	v_lshlrev_b32_e32 v28, 16, v29
	v_and_b32_e32 v29, 0xffff0000, v29
	v_pk_mul_f32 v[28:29], v[100:101], v[28:29] op_sel_hi:[0,1]
	v_pk_mul_f32 v[32:33], v[100:101], v[32:33] op_sel_hi:[0,1]
	v_div_fixup_f32 v26, v27, v26, 1.0
	v_pk_fma_f32 v[22:23], v[22:23], v[36:37], v[32:33] op_sel_hi:[1,0,1]
	v_pk_fma_f32 v[24:25], v[24:25], v[36:37], v[28:29] op_sel_hi:[1,0,1]
	v_pk_mul_f32 v[22:23], v[26:27], v[22:23] op_sel_hi:[0,1]
	v_pk_mul_f32 v[24:25], v[26:27], v[24:25] op_sel_hi:[0,1]
	v_cvt_pk_bf16_f32 v22, v22, v23
	v_cvt_pk_bf16_f32 v23, v24, v25
	v_lshlrev_b64 v[28:29], 12, v[98:99]
	v_lshl_add_u64 v[28:29], v[94:95], 0, v[28:29]
	v_and_b32_e32 v238, 16, v241
	v_lshrrev_b32_e32 v239, 1, v238
	v_add_u32_e32 v238, v238, v239
	v_mov_b32_e32 v239, 0
	v_lshl_add_u64 v[28:29], v[28:29], 0, v[238:239]
	s_waitcnt lgkmcnt(2)
	v_lshlrev_b32_e32 v228, 16, v222
	v_and_b32_e32 v229, 0xffff0000, v222
	v_lshlrev_b32_e32 v230, 16, v223
	v_and_b32_e32 v231, 0xffff0000, v223
	v_pk_mul_f32 v[230:231], v[100:101], v[230:231] op_sel_hi:[0,1]
	v_pk_mul_f32 v[228:229], v[100:101], v[228:229] op_sel_hi:[0,1]
	v_pk_fma_f32 v[18:19], v[18:19], v[36:37], v[228:229] op_sel_hi:[1,0,1]
	v_pk_fma_f32 v[20:21], v[20:21], v[36:37], v[230:231] op_sel_hi:[1,0,1]
	v_pk_mul_f32 v[18:19], v[26:27], v[18:19] op_sel_hi:[0,1]
	v_pk_mul_f32 v[20:21], v[26:27], v[20:21] op_sel_hi:[0,1]
	v_cvt_pk_bf16_f32 v24, v18, v19
	v_cvt_pk_bf16_f32 v25, v20, v21
	s_nop 1
	v_permlane16_swap_b32 v22, v24
	v_permlane16_swap_b32 v23, v25
	global_store_dwordx4 v[28:29], v[22:25], off offset:2048
	s_waitcnt lgkmcnt(1)
	v_lshlrev_b32_e32 v18, 16, v224
	v_and_b32_e32 v19, 0xffff0000, v224
	v_lshlrev_b32_e32 v20, 16, v225
	v_and_b32_e32 v21, 0xffff0000, v225
	v_pk_mul_f32 v[20:21], v[100:101], v[20:21] op_sel_hi:[0,1]
	v_pk_mul_f32 v[18:19], v[100:101], v[18:19] op_sel_hi:[0,1]
	v_pk_fma_f32 v[14:15], v[14:15], v[36:37], v[18:19] op_sel_hi:[1,0,1]
	v_pk_fma_f32 v[16:17], v[16:17], v[36:37], v[20:21] op_sel_hi:[1,0,1]
	v_pk_mul_f32 v[14:15], v[26:27], v[14:15] op_sel_hi:[0,1]
	v_pk_mul_f32 v[16:17], v[26:27], v[16:17] op_sel_hi:[0,1]
	v_cvt_pk_bf16_f32 v14, v14, v15
	v_cvt_pk_bf16_f32 v15, v16, v17
	s_waitcnt lgkmcnt(0)
	v_lshlrev_b32_e32 v228, 16, v226
	v_and_b32_e32 v229, 0xffff0000, v226
	v_lshlrev_b32_e32 v230, 16, v227
	v_and_b32_e32 v231, 0xffff0000, v227
	v_pk_mul_f32 v[228:229], v[100:101], v[228:229] op_sel_hi:[0,1]
	v_pk_mul_f32 v[230:231], v[100:101], v[230:231] op_sel_hi:[0,1]
	v_pk_fma_f32 v[10:11], v[10:11], v[36:37], v[228:229] op_sel_hi:[1,0,1]
	v_pk_fma_f32 v[12:13], v[12:13], v[36:37], v[230:231] op_sel_hi:[1,0,1]
	v_pk_mul_f32 v[10:11], v[26:27], v[10:11] op_sel_hi:[0,1]
	v_pk_mul_f32 v[12:13], v[26:27], v[12:13] op_sel_hi:[0,1]
	v_cvt_pk_bf16_f32 v16, v10, v11
	v_cvt_pk_bf16_f32 v17, v12, v13
	s_nop 1
	v_permlane16_swap_b32 v14, v16
	v_permlane16_swap_b32 v15, v17
	global_store_dwordx4 v[28:29], v[14:17], off offset:2112
